# P9 epilogue: nt on the never-re-read output stores only, on top of P6 residual nt
# baseline (speedup 1.0000x reference)
.LBB0_1022:
	s_ashr_i32 s23, s30, 5
	v_lshl_or_b32 v0, s55, 8, v182
	s_mul_hi_i32 s25, s23, 0x18000
	s_mul_i32 s23, s23, 0x18000
	s_add_u32 s36, s48, s23
	v_ashrrev_i32_e32 v1, 31, v0
	s_addc_u32 s37, s49, s25
	v_lshlrev_b64 v[0:1], 2, v[0:1]
	v_lshl_add_u64 v[10:11], s[36:37], 0, v[0:1]
	global_load_dwordx4 v[2:5], v[10:11], off
	global_load_dwordx4 v[6:9], v[10:11], off offset:64
	global_load_dwordx4 v[22:25], v[10:11], off offset:512
	global_load_dwordx4 v[26:29], v[10:11], off offset:576
	v_lshl_add_u32 v10, s30, 8, v180
	v_ashrrev_i32_e32 v11, 31, v10
	v_lshl_add_u64 v[18:19], s[4:5], 0, v[0:1]
	v_lshlrev_b64 v[20:21], 14, v[10:11]
	v_lshl_add_u64 v[12:13], v[18:19], 0, v[20:21]
	global_load_dwordx4 v[172:175], v[12:13], off
	global_load_dwordx4 v[176:179], v[12:13], off offset:64
	global_load_dwordx4 v[188:191], v[12:13], off offset:512
	global_load_dwordx4 v[192:195], v[12:13], off offset:576
	v_or_b32_e32 v12, 16, v10
	v_ashrrev_i32_e32 v13, 31, v12
	v_lshlrev_b64 v[12:13], 14, v[12:13]
	v_lshl_add_u64 v[14:15], v[18:19], 0, v[12:13]
	global_load_dwordx4 v[196:199], v[14:15], off
	global_load_dwordx4 v[200:203], v[14:15], off offset:64
	global_load_dwordx4 v[204:207], v[14:15], off offset:512
	global_load_dwordx4 v[208:211], v[14:15], off offset:576
	v_or_b32_e32 v14, 32, v10
	v_ashrrev_i32_e32 v15, 31, v14
	v_lshlrev_b64 v[14:15], 14, v[14:15]
	v_lshl_add_u64 v[16:17], v[18:19], 0, v[14:15]
	global_load_dwordx4 v[212:215], v[16:17], off
	global_load_dwordx4 v[216:219], v[16:17], off offset:64
	global_load_dwordx4 v[220:223], v[16:17], off offset:512
	v_or_b32_e32 v10, 48, v10
	global_load_dwordx4 v[224:227], v[16:17], off offset:576
	v_ashrrev_i32_e32 v11, 31, v10
	v_lshlrev_b64 v[244:245], 14, v[10:11]
	v_lshl_add_u64 v[10:11], v[18:19], 0, v[244:245]
	global_load_dwordx4 v[228:231], v[10:11], off
	global_load_dwordx4 v[232:235], v[10:11], off offset:64
	global_load_dwordx4 v[236:239], v[10:11], off offset:512
	global_load_dwordx4 v[240:243], v[10:11], off offset:576
	v_lshl_add_u64 v[10:11], s[4:5], 0, v[20:21]
	v_lshl_add_u64 v[246:247], v[10:11], 0, v[0:1]
	v_lshl_add_u64 v[10:11], s[4:5], 0, v[12:13]
	v_lshl_add_u64 v[12:13], s[4:5], 0, v[14:15]
	v_lshl_add_u64 v[248:249], v[10:11], 0, v[0:1]
	v_lshl_add_u64 v[250:251], v[12:13], 0, v[0:1]
	s_andn2_b64 vcc, exec, s[0:1]
	s_mov_b64 s[0:1], -1
	s_waitcnt vmcnt(0)
	v_pk_mul_f32 v[14:15], v[4:5], s[14:15] op_sel_hi:[1,0]
	v_pk_mul_f32 v[16:17], v[2:3], s[14:15] op_sel_hi:[1,0]
	v_pk_mul_f32 v[10:11], v[8:9], s[14:15] op_sel_hi:[1,0]
	v_pk_mul_f32 v[12:13], v[6:7], s[14:15] op_sel_hi:[1,0]
	v_pk_mul_f32 v[6:7], v[24:25], s[14:15] op_sel_hi:[1,0]
	v_pk_mul_f32 v[8:9], v[22:23], s[14:15] op_sel_hi:[1,0]
	v_pk_mul_f32 v[2:3], v[28:29], s[14:15] op_sel_hi:[1,0]
	v_pk_mul_f32 v[4:5], v[26:27], s[14:15] op_sel_hi:[1,0]
	v_pk_fma_f32 v[24:25], v[158:159], v[14:15], v[174:175]
	v_pk_fma_f32 v[22:23], v[156:157], v[16:17], v[172:173]
	v_pk_fma_f32 v[28:29], v[154:155], v[10:11], v[178:179]
	v_pk_fma_f32 v[26:27], v[152:153], v[12:13], v[176:177]
	v_pk_fma_f32 v[138:139], v[138:139], v[6:7], v[190:191]
	v_pk_fma_f32 v[136:137], v[136:137], v[8:9], v[188:189]
	v_pk_fma_f32 v[134:135], v[134:135], v[2:3], v[194:195]
	v_pk_fma_f32 v[132:133], v[132:133], v[4:5], v[192:193]
	v_pk_fma_f32 v[150:151], v[150:151], v[14:15], v[198:199]
	v_pk_fma_f32 v[148:149], v[148:149], v[16:17], v[196:197]
	v_pk_fma_f32 v[146:147], v[146:147], v[10:11], v[202:203]
	v_pk_fma_f32 v[144:145], v[144:145], v[12:13], v[200:201]
	v_pk_fma_f32 v[130:131], v[130:131], v[6:7], v[206:207]
	v_pk_fma_f32 v[128:129], v[128:129], v[8:9], v[204:205]
	v_pk_fma_f32 v[122:123], v[122:123], v[2:3], v[210:211]
	v_pk_fma_f32 v[120:121], v[120:121], v[4:5], v[208:209]
	v_pk_fma_f32 v[142:143], v[142:143], v[14:15], v[214:215]
	v_pk_fma_f32 v[140:141], v[140:141], v[16:17], v[212:213]
	global_store_dwordx4 v[246:247], v[22:25], off nt
	global_store_dwordx4 v[246:247], v[26:29], off offset:64 nt
	global_store_dwordx4 v[246:247], v[136:139], off offset:512 nt
	global_store_dwordx4 v[246:247], v[132:135], off offset:576 nt
	global_store_dwordx4 v[248:249], v[148:151], off nt
	global_store_dwordx4 v[248:249], v[144:147], off offset:64 nt
	global_store_dwordx4 v[248:249], v[128:131], off offset:512 nt
	global_store_dwordx4 v[248:249], v[120:123], off offset:576 nt
	global_store_dwordx4 v[250:251], v[140:143], off nt
	v_pk_fma_f32 v[24:25], v[114:115], v[6:7], v[222:223]
	v_pk_fma_f32 v[22:23], v[112:113], v[8:9], v[220:221]
	global_store_dwordx4 v[250:251], v[22:25], off offset:512 nt
	v_lshl_add_u64 v[26:27], s[4:5], 0, v[244:245]
	v_lshl_add_u64 v[26:27], v[26:27], 0, v[0:1]
	v_pk_fma_f32 v[24:25], v[106:107], v[2:3], v[226:227]
	v_pk_fma_f32 v[22:23], v[104:105], v[4:5], v[224:225]
	global_store_dwordx4 v[250:251], v[22:25], off offset:576 nt
	v_pk_fma_f32 v[30:31], v[126:127], v[10:11], v[218:219]
	v_pk_fma_f32 v[28:29], v[124:125], v[12:13], v[216:217]
	v_pk_fma_f32 v[24:25], v[118:119], v[14:15], v[230:231]
	v_pk_fma_f32 v[22:23], v[116:117], v[16:17], v[228:229]
	global_store_dwordx4 v[26:27], v[22:25], off nt
	global_store_dwordx4 v[250:251], v[28:31], off offset:64 nt
	v_lshl_add_u64 v[148:149], v[20:21], 0, s[16:17]
	v_pk_fma_f32 v[24:25], v[110:111], v[10:11], v[234:235]
	v_pk_fma_f32 v[22:23], v[108:109], v[12:13], v[232:233]
	global_store_dwordx4 v[26:27], v[22:25], off offset:64 nt
	v_lshl_add_u64 v[30:31], v[20:21], 0, s[8:9]
	v_lshl_add_u64 v[104:105], v[18:19], 0, v[30:31]
	v_pk_fma_f32 v[24:25], v[102:103], v[6:7], v[238:239]
	v_pk_fma_f32 v[22:23], v[100:101], v[8:9], v[236:237]
	global_store_dwordx4 v[26:27], v[22:25], off offset:512 nt
	v_lshl_add_u64 v[116:117], v[18:19], 0, v[148:149]
	v_lshl_add_u64 v[150:151], v[20:21], 0, s[18:19]
	v_pk_fma_f32 v[24:25], v[98:99], v[2:3], v[242:243]
	v_pk_fma_f32 v[22:23], v[96:97], v[4:5], v[240:241]
	global_store_dwordx4 v[26:27], v[22:25], off offset:576 nt
	v_lshl_add_u64 v[152:153], v[20:21], 0, s[20:21]
	global_load_dwordx4 v[22:25], v[104:105], off
	global_load_dwordx4 v[26:29], v[104:105], off offset:64
	global_load_dwordx4 v[96:99], v[104:105], off offset:512
	global_load_dwordx4 v[100:103], v[104:105], off offset:576
	s_nop 0
	global_load_dwordx4 v[104:107], v[116:117], off
	global_load_dwordx4 v[108:111], v[116:117], off offset:64
	global_load_dwordx4 v[112:115], v[116:117], off offset:512
	s_nop 0
	global_load_dwordx4 v[116:119], v[116:117], off offset:576
	v_lshl_add_u64 v[132:133], v[18:19], 0, v[150:151]
	v_lshl_add_u64 v[144:145], v[18:19], 0, v[152:153]
	global_load_dwordx4 v[120:123], v[132:133], off
	global_load_dwordx4 v[124:127], v[132:133], off offset:64
	global_load_dwordx4 v[128:131], v[132:133], off offset:512
	s_nop 0
	global_load_dwordx4 v[132:135], v[132:133], off offset:576
	s_nop 0
	global_load_dwordx4 v[18:21], v[144:145], off
	global_load_dwordx4 v[136:139], v[144:145], off offset:64
	global_load_dwordx4 v[140:143], v[144:145], off offset:512
	s_nop 0
	global_load_dwordx4 v[144:147], v[144:145], off offset:576
	v_lshl_add_u64 v[30:31], s[4:5], 0, v[30:31]
	v_lshl_add_u64 v[148:149], s[4:5], 0, v[148:149]
	v_lshl_add_u64 v[150:151], s[4:5], 0, v[150:151]
	v_lshl_add_u64 v[30:31], v[30:31], 0, v[0:1]
	v_lshl_add_u64 v[148:149], v[148:149], 0, v[0:1]
	v_lshl_add_u64 v[150:151], v[150:151], 0, v[0:1]
	s_waitcnt vmcnt(15)
	v_pk_fma_f32 v[24:25], v[94:95], v[14:15], v[24:25]
	v_pk_fma_f32 v[22:23], v[92:93], v[16:17], v[22:23]
	s_waitcnt vmcnt(14)
	v_pk_fma_f32 v[28:29], v[90:91], v[10:11], v[28:29]
	v_pk_fma_f32 v[26:27], v[88:89], v[12:13], v[26:27]
	s_waitcnt vmcnt(13)
	v_pk_fma_f32 v[74:75], v[74:75], v[6:7], v[98:99]
	v_pk_fma_f32 v[72:73], v[72:73], v[8:9], v[96:97]
	s_waitcnt vmcnt(12)
	v_pk_fma_f32 v[70:71], v[70:71], v[2:3], v[102:103]
	v_pk_fma_f32 v[68:69], v[68:69], v[4:5], v[100:101]
	s_waitcnt vmcnt(11)
	v_pk_fma_f32 v[86:87], v[86:87], v[14:15], v[106:107]
	v_pk_fma_f32 v[84:85], v[84:85], v[16:17], v[104:105]
	s_waitcnt vmcnt(10)
	v_pk_fma_f32 v[82:83], v[82:83], v[10:11], v[110:111]
	v_pk_fma_f32 v[80:81], v[80:81], v[12:13], v[108:109]
	s_waitcnt vmcnt(9)
	v_pk_fma_f32 v[62:63], v[62:63], v[6:7], v[114:115]
	v_pk_fma_f32 v[60:61], v[60:61], v[8:9], v[112:113]
	s_waitcnt vmcnt(8)
	v_pk_fma_f32 v[58:59], v[58:59], v[2:3], v[118:119]
	v_pk_fma_f32 v[56:57], v[56:57], v[4:5], v[116:117]
	s_waitcnt vmcnt(7)
	v_pk_fma_f32 v[78:79], v[78:79], v[14:15], v[122:123]
	v_pk_fma_f32 v[76:77], v[76:77], v[16:17], v[120:121]
	s_waitcnt vmcnt(6)
	v_pk_fma_f32 v[66:67], v[66:67], v[10:11], v[126:127]
	v_pk_fma_f32 v[64:65], v[64:65], v[12:13], v[124:125]
	global_store_dwordx4 v[30:31], v[22:25], off nt
	global_store_dwordx4 v[30:31], v[26:29], off offset:64 nt
	global_store_dwordx4 v[30:31], v[72:75], off offset:512 nt
	global_store_dwordx4 v[30:31], v[68:71], off offset:576 nt
	global_store_dwordx4 v[148:149], v[84:87], off nt
	global_store_dwordx4 v[148:149], v[80:83], off offset:64 nt
	global_store_dwordx4 v[148:149], v[60:63], off offset:512 nt
	global_store_dwordx4 v[148:149], v[56:59], off offset:576 nt
	global_store_dwordx4 v[150:151], v[76:79], off nt
	global_store_dwordx4 v[150:151], v[64:67], off offset:64 nt
	s_waitcnt vmcnt(15)
	v_pk_fma_f32 v[24:25], v[50:51], v[6:7], v[130:131]
	v_pk_fma_f32 v[22:23], v[48:49], v[8:9], v[128:129]
	s_waitcnt vmcnt(13)
	v_pk_fma_f32 v[20:21], v[54:55], v[14:15], v[20:21]
	v_lshl_add_u64 v[14:15], s[4:5], 0, v[152:153]
	global_store_dwordx4 v[150:151], v[22:25], off offset:512 nt
	v_pk_fma_f32 v[18:19], v[52:53], v[16:17], v[18:19]
	v_lshl_add_u64 v[16:17], v[14:15], 0, v[0:1]
	v_pk_fma_f32 v[24:25], v[42:43], v[2:3], v[134:135]
	v_pk_fma_f32 v[22:23], v[40:41], v[4:5], v[132:133]
	s_waitcnt vmcnt(13)
	v_pk_fma_f32 v[14:15], v[46:47], v[10:11], v[138:139]
	v_pk_fma_f32 v[12:13], v[44:45], v[12:13], v[136:137]
	s_waitcnt vmcnt(12)
	v_pk_fma_f32 v[10:11], v[38:39], v[6:7], v[142:143]
	v_pk_fma_f32 v[8:9], v[36:37], v[8:9], v[140:141]
	s_waitcnt vmcnt(11)
	v_pk_fma_f32 v[2:3], v[34:35], v[2:3], v[146:147]
	v_pk_fma_f32 v[0:1], v[32:33], v[4:5], v[144:145]
	global_store_dwordx4 v[150:151], v[22:25], off offset:576 nt
	global_store_dwordx4 v[16:17], v[18:21], off nt
	global_store_dwordx4 v[16:17], v[12:15], off offset:64 nt
	global_store_dwordx4 v[16:17], v[8:11], off offset:512 nt
	global_store_dwordx4 v[16:17], v[0:3], off offset:576 nt
	s_cbranch_vccnz .LBB0_1011
	s_nop 7
	s_andn2_b64 vcc, exec, s[10:11]
	s_cbranch_vccnz .LBB0_1010
	s_barrier
	s_branch .LBB0_1010
